# attention QK^T segment hand-scheduled: K-fragment LDS reads one key-row group ahead of the MFMAs, bias gathers behind them, counted lgkmcnt waits, dependent MFMA pairs interleaved
# baseline (speedup 1.0000x reference)
; #define LAS __attribute__((address_space(3)))
; #define MFMA16(a, b, c) __builtin_amdgcn_mfma_f32_16x16x32_bf16((a), (b), (c), 0, 0, 0)
; __device__ __forceinline__ int att_fk(int key) { return ((key >> 3) & 3) + 4 * ((key >> 1) & 1); }
; #define ATT_BAR() do { asm volatile("s_waitcnt lgkmcnt(0)" ::: "memory"); __builtin_amdgcn_s_barrier(); asm volatile("" ::: "memory"); } while (0)
; __device__ __forceinline__ void attn_phase(const bf16_t* Q, const bf16_t* Kb, const bf16_t* VTa, const float* rpb, bf16_t* Y, LAS unsigned char* lds, int bx, int G, int tid, int wave, int lane) {
;     ...
; #pragma unroll
;             for (int ii = 0; ii < 4; ++ii) {
;                 const int i = 4 * hf + ii, dr = rs + i - r + 7;
;                 float bia[8];
; #pragma unroll
;                 for (int j = 0; j < 8; ++j) bia[j] = rl[((unsigned)(j - wlo) < (unsigned)wwd) ? dr * 31 + dci0 + j : 480];
; #pragma unroll
;                 for (int ta = 0; ta < 2; ++ta) {
;                     const int key = cs + 8 * (fr >> 2) + 4 * ta + (fr & 3), fk = att_fk(key);
;                     const LAS unsigned char* kp = KL + ((rs + i) & 7) * 8192 + key * 128;
;                     const bf16x8 kf0 = *(const LAS bf16x8*)(kp + ((fq ^ fk) << 4)), kf1 = *(const LAS bf16x8*)(kp + (((4 + fq) ^ fk) << 4));
;                     f32x4 a = {0.f, 0.f, 0.f, 0.f};
;                     a = MFMA16(kf0, qf0, a); a = MFMA16(kf1, qf1, a);
; #pragma unroll
;                     for (int idx = 0; idx < 4; ++idx) { a[idx] += bia[4 * ta + idx]; mx = fmaxf(mx, a[idx]); }
;                     s[ii][ta] = a;
;                 }
;             }
;             ATT_BAR();
.Ltop1_d:
	v_lshl_add_u32 v190, v10, 2, s84
	v_cndmask_b32_e64 v11, v194, v190, s[40:41]
	v_add_u32_e32 v14, s75, v61
	s_waitcnt lgkmcnt(0)
	s_barrier
	s_add_i32 s59, s64, s89
	s_add_i32 vcc_hi, s61, 0xffffff46
	s_lshl_b32 s59, s59, 13
	s_and_b32 vcc_lo, s59, 0xe000
	s_add_i32 s59, s64, s90
	s_addk_i32 s61, 0xff65
	s_lshl_b32 s59, s59, 13
	s_and_b32 s60, s59, 0xe000
	s_add_i32 s58, s30, s58
	s_add_i32 s31, s64, s91
	s_mul_i32 s59, s58, 31
	s_addk_i32 s59, 0xff27
	s_lshl_b32 s31, s31, 13
	s_and_b32 s58, s31, 0xe000
	v_add_u32_e32 v158, s75, v61
	v_add_u32_e32 v150, v158, v55
	v_add_u32_e32 v151, v158, v41
	v_add_u32_e32 v158, vcc_lo, v61
	v_add_u32_e32 v152, v158, v55
	v_add_u32_e32 v153, v158, v41
	v_add_u32_e32 v158, s60, v61
	v_add_u32_e32 v154, v158, v55
	v_add_u32_e32 v155, v158, v41
	v_add_u32_e32 v158, s58, v61
	v_add_u32_e32 v156, v158, v55
	v_add_u32_e32 v157, v158, v41
	v_add_u32_e32 v158, vcc_hi, v46
	v_lshl_add_u32 v191, v158, 2, s84
	v_add_u32_e32 v158, s61, v46
	v_lshl_add_u32 v192, v158, 2, s84
	v_add_u32_e32 v158, s59, v46
	v_lshl_add_u32 v193, v158, 2, s84
	ds_read_b128 v[118:121], v151
	ds_read_b128 v[122:125], v150
	ds_read_b128 v[126:129], v151 offset:512
	ds_read_b128 v[130:133], v150 offset:512
	ds_read_b128 v[134:137], v153
	ds_read_b128 v[138:141], v152
	ds_read_b128 v[142:145], v153 offset:512
	ds_read_b128 v[146:149], v152 offset:512
	s_waitcnt lgkmcnt(4)
	v_mfma_f32_16x16x32_bf16 v[10:13], v[118:121], v[6:9], 0
	v_mfma_f32_16x16x32_bf16 v[14:17], v[126:129], v[6:9], 0
	v_mfma_f32_16x16x32_bf16 v[10:13], v[122:125], v[2:5], v[10:13]
	v_mfma_f32_16x16x32_bf16 v[14:17], v[130:133], v[2:5], v[14:17]
	v_cndmask_b32_e64 v158, v194, v190, s[40:41]
	ds_read_b32 v202, v158
	v_cndmask_b32_e64 v159, v195, v190, s[42:43]
	ds_read_b32 v203, v159 offset:4
	v_cndmask_b32_e64 v158, v196, v190, s[44:45]
	ds_read_b32 v204, v158 offset:8
	v_cndmask_b32_e64 v159, v197, v190, s[46:47]
	ds_read_b32 v205, v159 offset:12
	v_cndmask_b32_e64 v158, v198, v190, s[48:49]
	ds_read_b32 v206, v158 offset:16
	v_cndmask_b32_e64 v159, v199, v190, s[50:51]
	ds_read_b32 v207, v159 offset:20
	v_cndmask_b32_e64 v158, v200, v190, s[52:53]
	ds_read_b32 v208, v158 offset:24
	v_cndmask_b32_e64 v159, v201, v190, s[54:55]
	ds_read_b32 v209, v159 offset:28
	ds_read_b128 v[118:121], v155
	ds_read_b128 v[122:125], v154
	ds_read_b128 v[126:129], v155 offset:512
	ds_read_b128 v[130:133], v154 offset:512
	s_waitcnt lgkmcnt(12)
	v_mfma_f32_16x16x32_bf16 v[18:21], v[134:137], v[6:9], 0
	v_mfma_f32_16x16x32_bf16 v[22:25], v[142:145], v[6:9], 0
	v_mfma_f32_16x16x32_bf16 v[18:21], v[138:141], v[2:5], v[18:21]
	v_mfma_f32_16x16x32_bf16 v[22:25], v[146:149], v[2:5], v[22:25]
	v_cndmask_b32_e64 v158, v194, v191, s[40:41]
	ds_read_b32 v210, v158
	v_cndmask_b32_e64 v159, v195, v191, s[42:43]
	ds_read_b32 v211, v159 offset:4
	v_cndmask_b32_e64 v158, v196, v191, s[44:45]
	ds_read_b32 v212, v158 offset:8
	v_cndmask_b32_e64 v159, v197, v191, s[46:47]
	ds_read_b32 v213, v159 offset:12
	v_cndmask_b32_e64 v158, v198, v191, s[48:49]
	ds_read_b32 v214, v158 offset:16
	v_cndmask_b32_e64 v159, v199, v191, s[50:51]
	ds_read_b32 v215, v159 offset:20
	v_cndmask_b32_e64 v158, v200, v191, s[52:53]
	ds_read_b32 v216, v158 offset:24
	v_cndmask_b32_e64 v159, v201, v191, s[54:55]
	ds_read_b32 v217, v159 offset:28
	ds_read_b128 v[134:137], v157
	ds_read_b128 v[138:141], v156
	ds_read_b128 v[142:145], v157 offset:512
	ds_read_b128 v[146:149], v156 offset:512
	s_waitcnt lgkmcnt(12)
	v_mfma_f32_16x16x32_bf16 v[26:29], v[118:121], v[6:9], 0
	v_mfma_f32_16x16x32_bf16 v[30:33], v[126:129], v[6:9], 0
	v_mfma_f32_16x16x32_bf16 v[26:29], v[122:125], v[2:5], v[26:29]
	v_mfma_f32_16x16x32_bf16 v[30:33], v[130:133], v[2:5], v[30:33]
	v_cndmask_b32_e64 v158, v194, v192, s[40:41]
	ds_read_b32 v102, v158
	v_cndmask_b32_e64 v159, v195, v192, s[42:43]
	ds_read_b32 v103, v159 offset:4
	v_cndmask_b32_e64 v158, v196, v192, s[44:45]
	ds_read_b32 v104, v158 offset:8
	v_cndmask_b32_e64 v159, v197, v192, s[46:47]
	ds_read_b32 v105, v159 offset:12
	v_cndmask_b32_e64 v158, v198, v192, s[48:49]
	ds_read_b32 v106, v158 offset:16
	v_cndmask_b32_e64 v159, v199, v192, s[50:51]
	ds_read_b32 v107, v159 offset:20
	v_cndmask_b32_e64 v158, v200, v192, s[52:53]
	ds_read_b32 v108, v158 offset:24
	v_cndmask_b32_e64 v159, v201, v192, s[54:55]
	ds_read_b32 v109, v159 offset:28
	s_waitcnt lgkmcnt(8)
	v_mfma_f32_16x16x32_bf16 v[34:37], v[134:137], v[6:9], 0
	v_mfma_f32_16x16x32_bf16 v[34:37], v[138:141], v[2:5], v[34:37]
	v_cndmask_b32_e64 v158, v194, v193, s[40:41]
	ds_read_b32 v110, v158
	v_cndmask_b32_e64 v159, v195, v193, s[42:43]
	ds_read_b32 v111, v159 offset:4
	v_cndmask_b32_e64 v158, v196, v193, s[44:45]
	ds_read_b32 v112, v158 offset:8
	v_cndmask_b32_e64 v159, v197, v193, s[46:47]
	ds_read_b32 v113, v159 offset:12
	v_cndmask_b32_e64 v158, v198, v193, s[48:49]
	ds_read_b32 v114, v158 offset:16
	v_cndmask_b32_e64 v159, v199, v193, s[50:51]
	ds_read_b32 v115, v159 offset:20
	v_cndmask_b32_e64 v158, v200, v193, s[52:53]
	ds_read_b32 v116, v158 offset:24
	v_cndmask_b32_e64 v159, v201, v193, s[54:55]
	ds_read_b32 v117, v159 offset:28
	s_cmp_eq_u32 s80, s64
	s_waitcnt lgkmcnt(0)
	s_barrier
	v_mfma_f32_16x16x32_bf16 v[6:9], v[142:145], v[6:9], 0
	v_mfma_f32_16x16x32_bf16 v[2:5], v[146:149], v[2:5], v[6:9]
	s_nop 0
	s_cbranch_scc1 .LBB0_453
	s_lshl_b32 s31, s64, 17
	s_add_u32 s58, s21, s31
	s_addc_u32 s59, s83, 0
	s_nop 1
	v_lshl_add_u64 v[6:7], s[58:59], 0, v[50:51]
	v_lshl_add_u64 v[6:7], v[6:7], 0, s[22:23]
	s_lshl_b32 s31, s64, 13
	v_lshl_add_u64 v[6:7], v[6:7], 0, v[0:1]
	s_mov_b64 s[58:59], 0x100000
	s_and_b32 s31, s31, 0xe000
	v_lshl_add_u64 v[6:7], v[6:7], 0, s[58:59]
	s_add_i32 m0, s86, s31
	s_nop 0
	global_load_lds_dwordx4 v[6:7], off
